# barrier poll loops without s_sleep (tight polling of the top arrival counter)
# speedup vs baseline: 1.0000x; 1.0000x over previous
.LBB0_1136:
	s_and_b32 s20, s24, 0xff
	s_mov_b64 s[18:19], -1
	s_cmp_lg_u32 s20, 0
	s_mov_b64 s[22:23], -1
	s_cbranch_scc1 .LBB0_1139
	global_load_dword v2, v1, s[10:11] sc1
	s_waitcnt vmcnt(0)
	v_cmp_eq_u32_e32 vcc, 0, v2
	s_cbranch_vccnz .LBB0_1141
	s_mov_b64 s[22:23], 0
	s_mov_b64 s[20:21], -1

.LBB0_1153:
	s_and_b32 s18, s22, 0xff
	s_mov_b64 s[16:17], -1
	s_cmp_lg_u32 s18, 0
	s_mov_b64 s[20:21], -1
	s_cbranch_scc1 .LBB0_1156
	global_load_dword v2, v1, s[10:11] sc1
	s_waitcnt vmcnt(0)
	v_cmp_eq_u32_e32 vcc, 0, v2
	s_cbranch_vccnz .LBB0_1158
	s_mov_b64 s[20:21], 0
	s_mov_b64 s[18:19], -1
